# EpiResid residual epilogue: 32-step load-wait-fma-store ladder replaced by depth-3 pipelined batches (6 instances)
# speedup vs baseline: 1.0055x; 1.0055x over previous
.LBB0_394:
	s_add_i32 s2, s47, 0xffffff80
	s_ashr_i32 s20, s47, 31
	s_cmpk_lt_i32 s47, 0x80
	v_readlane_b32 s52, v239, 17
	s_cselect_b32 s21, s20, 0
	s_cselect_b32 s20, s47, s2
	v_readlane_b32 s53, v239, 18
	v_readlane_b32 s56, v239, 21
	v_readlane_b32 s57, v239, 22
	s_movk_i32 s23, 0x2400
	s_cselect_b32 s2, s87, s9
	s_cselect_b32 s22, s86, s8
	s_cselect_b32 s24, s53, s57
	s_cselect_b32 s25, s52, s56
	s_cselect_b32 s26, s23, 0x4800
	s_lshl_b64 s[20:21], s[20:21], 20
	s_add_u32 s22, s22, s20
	s_addc_u32 s23, s2, s21
	s_add_u32 s20, s25, s20
	s_addc_u32 s21, s24, s21
	s_cmp_gt_i32 s47, 63
	s_cselect_b32 s2, s26, 0
	v_lshl_or_b32 v158, s48, 8, v167
	s_lshl_b32 s2, s2, 2
	s_add_u32 s24, s37, s2
	v_ashrrev_i32_e32 v159, 31, v158
	s_addc_u32 s25, s38, 0
	v_lshlrev_b64 v[158:159], 2, v[158:159]
	v_lshl_add_u64 v[160:161], s[24:25], 0, v[158:159]
	v_lshl_add_u64 v[164:165], s[20:21], 0, v[158:159]
	v_lshlrev_b64 v[180:181], 2, v[134:135]
	global_load_dwordx4 v[172:175], v[160:161], off
	global_load_dwordx4 v[176:179], v[160:161], off offset:64
	global_load_dwordx4 v[182:185], v[160:161], off offset:512
	global_load_dwordx4 v[186:189], v[160:161], off offset:576
	v_lshl_add_u64 v[244:245], s[22:23], 0, v[158:159]
	v_lshl_add_u64 v[162:163], v[164:165], 0, v[180:181]
	global_load_dwordx4 v[190:193], v[162:163], off
	global_load_dwordx4 v[194:197], v[162:163], off offset:64
	global_load_dwordx4 v[198:201], v[162:163], off offset:512
	global_load_dwordx4 v[202:205], v[162:163], off offset:576
	v_lshl_add_u64 v[240:241], v[164:165], 0, v[144:145]
	global_load_dwordx4 v[206:209], v[240:241], off
	global_load_dwordx4 v[210:213], v[240:241], off offset:64
	global_load_dwordx4 v[214:217], v[240:241], off offset:512
	global_load_dwordx4 v[218:221], v[240:241], off offset:576
	v_lshl_add_u64 v[242:243], v[164:165], 0, v[146:147]
	global_load_dwordx4 v[222:225], v[242:243], off
	global_load_dwordx4 v[226:229], v[242:243], off offset:64
	global_load_dwordx4 v[230:233], v[242:243], off offset:512
	global_load_dwordx4 v[234:237], v[242:243], off offset:576
	s_waitcnt vmcnt(8)
	v_pk_mul_f32 v[172:173], v[172:173], 0.5 op_sel_hi:[1,0]
	v_pk_mul_f32 v[174:175], v[174:175], 0.5 op_sel_hi:[1,0]
	v_pk_mul_f32 v[176:177], v[176:177], 0.5 op_sel_hi:[1,0]
	v_pk_mul_f32 v[178:179], v[178:179], 0.5 op_sel_hi:[1,0]
	v_pk_mul_f32 v[182:183], v[182:183], 0.5 op_sel_hi:[1,0]
	v_pk_mul_f32 v[184:185], v[184:185], 0.5 op_sel_hi:[1,0]
	v_pk_mul_f32 v[186:187], v[186:187], 0.5 op_sel_hi:[1,0]
	v_pk_mul_f32 v[188:189], v[188:189], 0.5 op_sel_hi:[1,0]
	v_lshl_add_u64 v[162:163], v[244:245], 0, v[180:181]
	v_pk_fma_f32 v[190:191], v[126:127], v[172:173], v[190:191]
	v_pk_fma_f32 v[192:193], v[128:129], v[174:175], v[192:193]
	v_pk_fma_f32 v[194:195], v[122:123], v[176:177], v[194:195]
	v_pk_fma_f32 v[196:197], v[124:125], v[178:179], v[196:197]
	v_pk_fma_f32 v[198:199], v[118:119], v[182:183], v[198:199]
	v_pk_fma_f32 v[200:201], v[120:121], v[184:185], v[200:201]
	v_pk_fma_f32 v[202:203], v[106:107], v[186:187], v[202:203]
	v_pk_fma_f32 v[204:205], v[108:109], v[188:189], v[204:205]
	global_store_dwordx4 v[162:163], v[190:193], off
	global_store_dwordx4 v[162:163], v[194:197], off offset:64
	global_store_dwordx4 v[162:163], v[198:201], off offset:512
	global_store_dwordx4 v[162:163], v[202:205], off offset:576
	v_lshl_add_u64 v[162:163], v[164:165], 0, v[148:149]
	global_load_dwordx4 v[190:193], v[162:163], off
	global_load_dwordx4 v[194:197], v[162:163], off offset:64
	global_load_dwordx4 v[198:201], v[162:163], off offset:512
	global_load_dwordx4 v[202:205], v[162:163], off offset:576
	s_waitcnt vmcnt(12)
	v_lshl_add_u64 v[240:241], v[244:245], 0, v[144:145]
	v_pk_fma_f32 v[206:207], v[114:115], v[172:173], v[206:207]
	v_pk_fma_f32 v[208:209], v[116:117], v[174:175], v[208:209]
	v_pk_fma_f32 v[210:211], v[110:111], v[176:177], v[210:211]
	v_pk_fma_f32 v[212:213], v[112:113], v[178:179], v[212:213]
	v_pk_fma_f32 v[214:215], v[102:103], v[182:183], v[214:215]
	v_pk_fma_f32 v[216:217], v[104:105], v[184:185], v[216:217]
	v_pk_fma_f32 v[218:219], v[90:91], v[186:187], v[218:219]
	v_pk_fma_f32 v[220:221], v[92:93], v[188:189], v[220:221]
	global_store_dwordx4 v[240:241], v[206:209], off
	global_store_dwordx4 v[240:241], v[210:213], off offset:64
	global_store_dwordx4 v[240:241], v[214:217], off offset:512
	global_store_dwordx4 v[240:241], v[218:221], off offset:576
	v_lshl_add_u64 v[240:241], v[164:165], 0, v[150:151]
	global_load_dwordx4 v[206:209], v[240:241], off
	global_load_dwordx4 v[210:213], v[240:241], off offset:64
	global_load_dwordx4 v[214:217], v[240:241], off offset:512
	global_load_dwordx4 v[218:221], v[240:241], off offset:576
	s_waitcnt vmcnt(16)
	v_lshl_add_u64 v[242:243], v[244:245], 0, v[146:147]
	v_pk_fma_f32 v[222:223], v[98:99], v[172:173], v[222:223]
	v_pk_fma_f32 v[224:225], v[100:101], v[174:175], v[224:225]
	v_pk_fma_f32 v[226:227], v[94:95], v[176:177], v[226:227]
	v_pk_fma_f32 v[228:229], v[96:97], v[178:179], v[228:229]
	v_pk_fma_f32 v[230:231], v[86:87], v[182:183], v[230:231]
	v_pk_fma_f32 v[232:233], v[88:89], v[184:185], v[232:233]
	v_pk_fma_f32 v[234:235], v[74:75], v[186:187], v[234:235]
	v_pk_fma_f32 v[236:237], v[76:77], v[188:189], v[236:237]
	global_store_dwordx4 v[242:243], v[222:225], off
	global_store_dwordx4 v[242:243], v[226:229], off offset:64
	global_store_dwordx4 v[242:243], v[230:233], off offset:512
	global_store_dwordx4 v[242:243], v[234:237], off offset:576
	v_lshl_add_u64 v[242:243], v[164:165], 0, v[152:153]
	global_load_dwordx4 v[222:225], v[242:243], off
	global_load_dwordx4 v[226:229], v[242:243], off offset:64
	global_load_dwordx4 v[230:233], v[242:243], off offset:512
	global_load_dwordx4 v[234:237], v[242:243], off offset:576
	s_waitcnt vmcnt(16)
	v_lshl_add_u64 v[162:163], v[244:245], 0, v[148:149]
	v_pk_fma_f32 v[190:191], v[82:83], v[172:173], v[190:191]
	v_pk_fma_f32 v[192:193], v[84:85], v[174:175], v[192:193]
	v_pk_fma_f32 v[194:195], v[78:79], v[176:177], v[194:195]
	v_pk_fma_f32 v[196:197], v[80:81], v[178:179], v[196:197]
	v_pk_fma_f32 v[198:199], v[70:71], v[182:183], v[198:199]
	v_pk_fma_f32 v[200:201], v[72:73], v[184:185], v[200:201]
	v_pk_fma_f32 v[202:203], v[66:67], v[186:187], v[202:203]
	v_pk_fma_f32 v[204:205], v[68:69], v[188:189], v[204:205]
	global_store_dwordx4 v[162:163], v[190:193], off
	global_store_dwordx4 v[162:163], v[194:197], off offset:64
	global_store_dwordx4 v[162:163], v[198:201], off offset:512
	global_store_dwordx4 v[162:163], v[202:205], off offset:576
	v_lshl_add_u64 v[162:163], v[164:165], 0, v[154:155]
	global_load_dwordx4 v[190:193], v[162:163], off
	global_load_dwordx4 v[194:197], v[162:163], off offset:64
	global_load_dwordx4 v[198:201], v[162:163], off offset:512
	global_load_dwordx4 v[202:205], v[162:163], off offset:576
	s_waitcnt vmcnt(16)
	v_lshl_add_u64 v[240:241], v[244:245], 0, v[150:151]
	v_pk_fma_f32 v[206:207], v[62:63], v[172:173], v[206:207]
	v_pk_fma_f32 v[208:209], v[64:65], v[174:175], v[208:209]
	v_pk_fma_f32 v[210:211], v[58:59], v[176:177], v[210:211]
	v_pk_fma_f32 v[212:213], v[60:61], v[178:179], v[212:213]
	v_pk_fma_f32 v[214:215], v[54:55], v[182:183], v[214:215]
	v_pk_fma_f32 v[216:217], v[56:57], v[184:185], v[216:217]
	v_pk_fma_f32 v[218:219], v[42:43], v[186:187], v[218:219]
	v_pk_fma_f32 v[220:221], v[44:45], v[188:189], v[220:221]
	global_store_dwordx4 v[240:241], v[206:209], off
	global_store_dwordx4 v[240:241], v[210:213], off offset:64
	global_store_dwordx4 v[240:241], v[214:217], off offset:512
	global_store_dwordx4 v[240:241], v[218:221], off offset:576
	v_lshl_add_u64 v[240:241], v[164:165], 0, v[156:157]
	global_load_dwordx4 v[206:209], v[240:241], off
	global_load_dwordx4 v[210:213], v[240:241], off offset:64
	global_load_dwordx4 v[214:217], v[240:241], off offset:512
	global_load_dwordx4 v[218:221], v[240:241], off offset:576
	s_waitcnt vmcnt(16)
	v_lshl_add_u64 v[242:243], v[244:245], 0, v[152:153]
	v_pk_fma_f32 v[222:223], v[50:51], v[172:173], v[222:223]
	v_pk_fma_f32 v[224:225], v[52:53], v[174:175], v[224:225]
	v_pk_fma_f32 v[226:227], v[46:47], v[176:177], v[226:227]
	v_pk_fma_f32 v[228:229], v[48:49], v[178:179], v[228:229]
	v_pk_fma_f32 v[230:231], v[38:39], v[182:183], v[230:231]
	v_pk_fma_f32 v[232:233], v[40:41], v[184:185], v[232:233]
	v_pk_fma_f32 v[234:235], v[26:27], v[186:187], v[234:235]
	v_pk_fma_f32 v[236:237], v[28:29], v[188:189], v[236:237]
	global_store_dwordx4 v[242:243], v[222:225], off
	global_store_dwordx4 v[242:243], v[226:229], off offset:64
	global_store_dwordx4 v[242:243], v[230:233], off offset:512
	global_store_dwordx4 v[242:243], v[234:237], off offset:576
	s_waitcnt vmcnt(12)
	v_lshl_add_u64 v[162:163], v[244:245], 0, v[154:155]
	v_pk_fma_f32 v[190:191], v[34:35], v[172:173], v[190:191]
	v_pk_fma_f32 v[192:193], v[36:37], v[174:175], v[192:193]
	v_pk_fma_f32 v[194:195], v[30:31], v[176:177], v[194:195]
	v_pk_fma_f32 v[196:197], v[32:33], v[178:179], v[196:197]
	v_pk_fma_f32 v[198:199], v[22:23], v[182:183], v[198:199]
	v_pk_fma_f32 v[200:201], v[24:25], v[184:185], v[200:201]
	v_pk_fma_f32 v[202:203], v[10:11], v[186:187], v[202:203]
	v_pk_fma_f32 v[204:205], v[12:13], v[188:189], v[204:205]
	global_store_dwordx4 v[162:163], v[190:193], off
	global_store_dwordx4 v[162:163], v[194:197], off offset:64
	global_store_dwordx4 v[162:163], v[198:201], off offset:512
	global_store_dwordx4 v[162:163], v[202:205], off offset:576
	s_waitcnt vmcnt(8)
	v_lshl_add_u64 v[240:241], v[244:245], 0, v[156:157]
	v_pk_fma_f32 v[206:207], v[18:19], v[172:173], v[206:207]
	v_pk_fma_f32 v[208:209], v[20:21], v[174:175], v[208:209]
	v_pk_fma_f32 v[210:211], v[14:15], v[176:177], v[210:211]
	v_pk_fma_f32 v[212:213], v[16:17], v[178:179], v[212:213]
	v_pk_fma_f32 v[214:215], v[6:7], v[182:183], v[214:215]
	v_pk_fma_f32 v[216:217], v[8:9], v[184:185], v[216:217]
	v_pk_fma_f32 v[218:219], v[2:3], v[186:187], v[218:219]
	v_pk_fma_f32 v[220:221], v[4:5], v[188:189], v[220:221]
	global_store_dwordx4 v[240:241], v[206:209], off
	global_store_dwordx4 v[240:241], v[210:213], off offset:64
	global_store_dwordx4 v[240:241], v[214:217], off offset:512
	global_store_dwordx4 v[240:241], v[218:221], off offset:576
	s_and_b64 vcc, exec, s[4:5]
	s_mov_b64 s[4:5], -1
	v_readlane_b32 s54, v239, 19
	v_readlane_b32 s55, v239, 20
	v_readlane_b32 s58, v239, 23
	v_readlane_b32 s59, v239, 24
	v_readlane_b32 s60, v239, 25
	v_readlane_b32 s61, v239, 26
	v_readlane_b32 s62, v239, 27
	v_readlane_b32 s63, v239, 28
	v_readlane_b32 s64, v239, 29
	v_readlane_b32 s65, v239, 30
	v_readlane_b32 s66, v239, 31
	v_readlane_b32 s67, v239, 32
	s_cbranch_vccnz .LBB0_379
	s_andn2_b64 vcc, exec, s[12:13]
	s_cbranch_vccnz .LBB0_378
	s_barrier
	s_branch .LBB0_378

.LBB0_1104:
	s_add_i32 s2, s24, 0xffffff80
	s_ashr_i32 s17, s24, 31
	s_cmpk_lt_i32 s24, 0x80
	s_cselect_b32 s27, s17, 0
	s_cselect_b32 s26, s24, s2
	s_movk_i32 s19, 0x2400
	s_cselect_b32 s2, s87, s7
	s_cselect_b32 s17, s86, s6
	s_cselect_b32 s19, s19, 0x4800
	s_lshl_b64 s[26:27], s[26:27], 20
	s_add_u32 s26, s17, s26
	s_addc_u32 s27, s2, s27
	s_cmp_gt_i32 s24, 63
	s_cselect_b32 s2, s19, 0
	v_lshl_or_b32 v58, s25, 8, v177
	s_lshl_b32 s2, s2, 2
	s_add_u32 s24, s43, s2
	v_ashrrev_i32_e32 v59, 31, v58
	s_addc_u32 s25, s44, 0
	v_lshlrev_b64 v[174:175], 2, v[58:59]
	v_lshl_add_u64 v[58:59], s[24:25], 0, v[174:175]
	v_lshl_add_u64 v[174:175], s[26:27], 0, v[174:175]
	v_lshl_add_u64 v[186:187], v[174:175], 0, v[150:151]
	global_load_dwordx4 v[110:113], v[58:59], off
	global_load_dwordx4 v[114:117], v[58:59], off offset:64
	global_load_dwordx4 v[122:125], v[58:59], off offset:512
	global_load_dwordx4 v[182:185], v[58:59], off offset:576
	global_load_dwordx4 v[188:191], v[186:187], off
	global_load_dwordx4 v[192:195], v[186:187], off offset:64
	global_load_dwordx4 v[196:199], v[186:187], off offset:512
	global_load_dwordx4 v[200:203], v[186:187], off offset:576
	v_lshl_add_u64 v[236:237], v[174:175], 0, v[160:161]
	global_load_dwordx4 v[204:207], v[236:237], off
	global_load_dwordx4 v[208:211], v[236:237], off offset:64
	global_load_dwordx4 v[212:215], v[236:237], off offset:512
	global_load_dwordx4 v[216:219], v[236:237], off offset:576
	v_lshl_add_u64 v[240:241], v[174:175], 0, v[162:163]
	global_load_dwordx4 v[220:223], v[240:241], off
	global_load_dwordx4 v[224:227], v[240:241], off offset:64
	global_load_dwordx4 v[228:231], v[240:241], off offset:512
	global_load_dwordx4 v[232:235], v[240:241], off offset:576
	s_waitcnt vmcnt(8)
	v_pk_fma_f32 v[188:189], v[142:143], v[110:111], v[188:189]
	v_pk_fma_f32 v[190:191], v[144:145], v[112:113], v[190:191]
	v_pk_fma_f32 v[192:193], v[138:139], v[114:115], v[192:193]
	v_pk_fma_f32 v[194:195], v[140:141], v[116:117], v[194:195]
	v_pk_fma_f32 v[196:197], v[134:135], v[122:123], v[196:197]
	v_pk_fma_f32 v[198:199], v[136:137], v[124:125], v[198:199]
	v_pk_fma_f32 v[200:201], v[126:127], v[182:183], v[200:201]
	v_pk_fma_f32 v[202:203], v[128:129], v[184:185], v[202:203]
	global_store_dwordx4 v[186:187], v[188:191], off
	global_store_dwordx4 v[186:187], v[192:195], off offset:64
	global_store_dwordx4 v[186:187], v[196:199], off offset:512
	global_store_dwordx4 v[186:187], v[200:203], off offset:576
	v_lshl_add_u64 v[60:61], v[174:175], 0, v[164:165]
	global_load_dwordx4 v[188:191], v[60:61], off
	global_load_dwordx4 v[192:195], v[60:61], off offset:64
	global_load_dwordx4 v[196:199], v[60:61], off offset:512
	global_load_dwordx4 v[200:203], v[60:61], off offset:576
	s_waitcnt vmcnt(12)
	v_pk_fma_f32 v[204:205], v[130:131], v[110:111], v[204:205]
	v_pk_fma_f32 v[206:207], v[132:133], v[112:113], v[206:207]
	v_pk_fma_f32 v[208:209], v[118:119], v[114:115], v[208:209]
	v_pk_fma_f32 v[210:211], v[120:121], v[116:117], v[210:211]
	v_pk_fma_f32 v[212:213], v[106:107], v[122:123], v[212:213]
	v_pk_fma_f32 v[214:215], v[108:109], v[124:125], v[214:215]
	v_pk_fma_f32 v[216:217], v[98:99], v[182:183], v[216:217]
	v_pk_fma_f32 v[218:219], v[100:101], v[184:185], v[218:219]
	global_store_dwordx4 v[236:237], v[204:207], off
	global_store_dwordx4 v[236:237], v[208:211], off offset:64
	global_store_dwordx4 v[236:237], v[212:215], off offset:512
	global_store_dwordx4 v[236:237], v[216:219], off offset:576
	v_lshl_add_u64 v[236:237], v[174:175], 0, v[152:153]
	global_load_dwordx4 v[204:207], v[236:237], off
	global_load_dwordx4 v[208:211], v[236:237], off offset:64
	global_load_dwordx4 v[212:215], v[236:237], off offset:512
	global_load_dwordx4 v[216:219], v[236:237], off offset:576
	s_waitcnt vmcnt(16)
	v_pk_fma_f32 v[220:221], v[102:103], v[110:111], v[220:221]
	v_pk_fma_f32 v[222:223], v[104:105], v[112:113], v[222:223]
	v_pk_fma_f32 v[224:225], v[94:95], v[114:115], v[224:225]
	v_pk_fma_f32 v[226:227], v[96:97], v[116:117], v[226:227]
	v_pk_fma_f32 v[228:229], v[90:91], v[122:123], v[228:229]
	v_pk_fma_f32 v[230:231], v[92:93], v[124:125], v[230:231]
	v_pk_fma_f32 v[232:233], v[82:83], v[182:183], v[232:233]
	v_pk_fma_f32 v[234:235], v[84:85], v[184:185], v[234:235]
	global_store_dwordx4 v[240:241], v[220:223], off
	global_store_dwordx4 v[240:241], v[224:227], off offset:64
	global_store_dwordx4 v[240:241], v[228:231], off offset:512
	global_store_dwordx4 v[240:241], v[232:235], off offset:576
	v_lshl_add_u64 v[240:241], v[174:175], 0, v[154:155]
	global_load_dwordx4 v[220:223], v[240:241], off
	global_load_dwordx4 v[224:227], v[240:241], off offset:64
	global_load_dwordx4 v[228:231], v[240:241], off offset:512
	global_load_dwordx4 v[232:235], v[240:241], off offset:576
	s_waitcnt vmcnt(16)
	v_pk_fma_f32 v[188:189], v[86:87], v[110:111], v[188:189]
	v_pk_fma_f32 v[190:191], v[88:89], v[112:113], v[190:191]
	v_pk_fma_f32 v[192:193], v[78:79], v[114:115], v[192:193]
	v_pk_fma_f32 v[194:195], v[80:81], v[116:117], v[194:195]
	v_pk_fma_f32 v[196:197], v[74:75], v[122:123], v[196:197]
	v_pk_fma_f32 v[198:199], v[76:77], v[124:125], v[198:199]
	v_pk_fma_f32 v[200:201], v[70:71], v[182:183], v[200:201]
	v_pk_fma_f32 v[202:203], v[72:73], v[184:185], v[202:203]
	global_store_dwordx4 v[60:61], v[188:191], off
	global_store_dwordx4 v[60:61], v[192:195], off offset:64
	global_store_dwordx4 v[60:61], v[196:199], off offset:512
	global_store_dwordx4 v[60:61], v[200:203], off offset:576
	v_lshl_add_u64 v[60:61], v[174:175], 0, v[156:157]
	global_load_dwordx4 v[188:191], v[60:61], off
	global_load_dwordx4 v[192:195], v[60:61], off offset:64
	global_load_dwordx4 v[196:199], v[60:61], off offset:512
	global_load_dwordx4 v[200:203], v[60:61], off offset:576
	s_waitcnt vmcnt(16)
	v_pk_fma_f32 v[204:205], v[66:67], v[110:111], v[204:205]
	v_pk_fma_f32 v[206:207], v[68:69], v[112:113], v[206:207]
	v_pk_fma_f32 v[208:209], v[62:63], v[114:115], v[208:209]
	v_pk_fma_f32 v[210:211], v[64:65], v[116:117], v[210:211]
	v_pk_fma_f32 v[212:213], v[54:55], v[122:123], v[212:213]
	v_pk_fma_f32 v[214:215], v[56:57], v[124:125], v[214:215]
	v_pk_fma_f32 v[216:217], v[50:51], v[182:183], v[216:217]
	v_pk_fma_f32 v[218:219], v[52:53], v[184:185], v[218:219]
	global_store_dwordx4 v[236:237], v[204:207], off
	global_store_dwordx4 v[236:237], v[208:211], off offset:64
	global_store_dwordx4 v[236:237], v[212:215], off offset:512
	global_store_dwordx4 v[236:237], v[216:219], off offset:576
	v_lshl_add_u64 v[236:237], v[174:175], 0, v[158:159]
	global_load_dwordx4 v[204:207], v[236:237], off
	global_load_dwordx4 v[208:211], v[236:237], off offset:64
	global_load_dwordx4 v[212:215], v[236:237], off offset:512
	global_load_dwordx4 v[216:219], v[236:237], off offset:576
	s_waitcnt vmcnt(16)
	v_pk_fma_f32 v[220:221], v[46:47], v[110:111], v[220:221]
	v_pk_fma_f32 v[222:223], v[48:49], v[112:113], v[222:223]
	v_pk_fma_f32 v[224:225], v[42:43], v[114:115], v[224:225]
	v_pk_fma_f32 v[226:227], v[44:45], v[116:117], v[226:227]
	v_pk_fma_f32 v[228:229], v[38:39], v[122:123], v[228:229]
	v_pk_fma_f32 v[230:231], v[40:41], v[124:125], v[230:231]
	v_pk_fma_f32 v[232:233], v[34:35], v[182:183], v[232:233]
	v_pk_fma_f32 v[234:235], v[36:37], v[184:185], v[234:235]
	global_store_dwordx4 v[240:241], v[220:223], off
	global_store_dwordx4 v[240:241], v[224:227], off offset:64
	global_store_dwordx4 v[240:241], v[228:231], off offset:512
	global_store_dwordx4 v[240:241], v[232:235], off offset:576
	s_waitcnt vmcnt(12)
	v_pk_fma_f32 v[188:189], v[30:31], v[110:111], v[188:189]
	v_pk_fma_f32 v[190:191], v[32:33], v[112:113], v[190:191]
	v_pk_fma_f32 v[192:193], v[26:27], v[114:115], v[192:193]
	v_pk_fma_f32 v[194:195], v[28:29], v[116:117], v[194:195]
	v_pk_fma_f32 v[196:197], v[22:23], v[122:123], v[196:197]
	v_pk_fma_f32 v[198:199], v[24:25], v[124:125], v[198:199]
	v_pk_fma_f32 v[200:201], v[18:19], v[182:183], v[200:201]
	v_pk_fma_f32 v[202:203], v[20:21], v[184:185], v[202:203]
	global_store_dwordx4 v[60:61], v[188:191], off
	global_store_dwordx4 v[60:61], v[192:195], off offset:64
	global_store_dwordx4 v[60:61], v[196:199], off offset:512
	global_store_dwordx4 v[60:61], v[200:203], off offset:576
	s_waitcnt vmcnt(8)
	v_pk_fma_f32 v[204:205], v[14:15], v[110:111], v[204:205]
	v_pk_fma_f32 v[206:207], v[16:17], v[112:113], v[206:207]
	v_pk_fma_f32 v[208:209], v[10:11], v[114:115], v[208:209]
	v_pk_fma_f32 v[210:211], v[12:13], v[116:117], v[210:211]
	v_pk_fma_f32 v[212:213], v[6:7], v[122:123], v[212:213]
	v_pk_fma_f32 v[214:215], v[8:9], v[124:125], v[214:215]
	v_pk_fma_f32 v[216:217], v[2:3], v[182:183], v[216:217]
	v_pk_fma_f32 v[218:219], v[4:5], v[184:185], v[218:219]
	global_store_dwordx4 v[236:237], v[204:207], off
	global_store_dwordx4 v[236:237], v[208:211], off offset:64
	global_store_dwordx4 v[236:237], v[212:215], off offset:512
	global_store_dwordx4 v[236:237], v[216:219], off offset:576
	s_mov_b64 s[24:25], -1
	s_andn2_b64 vcc, exec, s[4:5]
	s_cbranch_vccnz .LBB0_1093
	s_andn2_b64 vcc, exec, s[10:11]
	s_cbranch_vccnz .LBB0_1092
	s_barrier
	s_branch .LBB0_1092

.LBB0_1370:
	s_add_i32 s2, s47, 0xffffff80
	s_ashr_i32 s20, s47, 31
	s_cmpk_lt_i32 s47, 0x80
	s_cselect_b32 s21, s20, 0
	s_cselect_b32 s20, s47, s2
	s_movk_i32 s23, 0x2400
	s_cselect_b32 s2, s87, s9
	s_cselect_b32 s22, s86, s8
	s_cselect_b32 s23, s23, 0x4800
	s_lshl_b64 s[20:21], s[20:21], 20
	s_add_u32 s20, s22, s20
	s_addc_u32 s21, s2, s21
	s_cmp_gt_i32 s47, 63
	s_cselect_b32 s2, s23, 0
	v_lshl_or_b32 v158, s48, 8, v177
	s_lshl_b32 s2, s2, 2
	s_add_u32 s22, s37, s2
	v_ashrrev_i32_e32 v159, 31, v158
	s_addc_u32 s23, s38, 0
	v_lshlrev_b64 v[174:175], 2, v[158:159]
	v_lshl_add_u64 v[182:183], s[22:23], 0, v[174:175]
	global_load_dwordx4 v[158:161], v[182:183], off
	global_load_dwordx4 v[162:165], v[182:183], off offset:64
	global_load_dwordx4 v[166:169], v[182:183], off offset:512
	global_load_dwordx4 v[170:173], v[182:183], off offset:576
	v_lshl_add_u64 v[240:241], s[20:21], 0, v[174:175]
	v_lshl_add_u64 v[232:233], v[240:241], 0, v[134:135]
	global_load_dwordx4 v[184:187], v[232:233], off
	global_load_dwordx4 v[188:191], v[232:233], off offset:64
	global_load_dwordx4 v[192:195], v[232:233], off offset:512
	global_load_dwordx4 v[196:199], v[232:233], off offset:576
	v_lshl_add_u64 v[234:235], v[240:241], 0, v[144:145]
	global_load_dwordx4 v[200:203], v[234:235], off
	global_load_dwordx4 v[204:207], v[234:235], off offset:64
	global_load_dwordx4 v[208:211], v[234:235], off offset:512
	global_load_dwordx4 v[212:215], v[234:235], off offset:576
	v_lshl_add_u64 v[236:237], v[240:241], 0, v[146:147]
	global_load_dwordx4 v[216:219], v[236:237], off
	global_load_dwordx4 v[220:223], v[236:237], off offset:64
	global_load_dwordx4 v[224:227], v[236:237], off offset:512
	global_load_dwordx4 v[228:231], v[236:237], off offset:576
	s_waitcnt vmcnt(8)
	v_pk_mul_f32 v[158:159], v[158:159], 0.5 op_sel_hi:[1,0]
	v_pk_mul_f32 v[160:161], v[160:161], 0.5 op_sel_hi:[1,0]
	v_pk_mul_f32 v[162:163], v[162:163], 0.5 op_sel_hi:[1,0]
	v_pk_mul_f32 v[164:165], v[164:165], 0.5 op_sel_hi:[1,0]
	v_pk_mul_f32 v[166:167], v[166:167], 0.5 op_sel_hi:[1,0]
	v_pk_mul_f32 v[168:169], v[168:169], 0.5 op_sel_hi:[1,0]
	v_pk_mul_f32 v[170:171], v[170:171], 0.5 op_sel_hi:[1,0]
	v_pk_mul_f32 v[172:173], v[172:173], 0.5 op_sel_hi:[1,0]
	v_pk_fma_f32 v[184:185], v[126:127], v[158:159], v[184:185]
	v_pk_fma_f32 v[186:187], v[128:129], v[160:161], v[186:187]
	v_pk_fma_f32 v[188:189], v[122:123], v[162:163], v[188:189]
	v_pk_fma_f32 v[190:191], v[124:125], v[164:165], v[190:191]
	v_pk_fma_f32 v[192:193], v[118:119], v[166:167], v[192:193]
	v_pk_fma_f32 v[194:195], v[120:121], v[168:169], v[194:195]
	v_pk_fma_f32 v[196:197], v[110:111], v[170:171], v[196:197]
	v_pk_fma_f32 v[198:199], v[112:113], v[172:173], v[198:199]
	global_store_dwordx4 v[232:233], v[184:187], off
	global_store_dwordx4 v[232:233], v[188:191], off offset:64
	global_store_dwordx4 v[232:233], v[192:195], off offset:512
	global_store_dwordx4 v[232:233], v[196:199], off offset:576
	v_lshl_add_u64 v[232:233], v[240:241], 0, v[148:149]
	global_load_dwordx4 v[184:187], v[232:233], off
	global_load_dwordx4 v[188:191], v[232:233], off offset:64
	global_load_dwordx4 v[192:195], v[232:233], off offset:512
	global_load_dwordx4 v[196:199], v[232:233], off offset:576
	s_waitcnt vmcnt(12)
	v_pk_fma_f32 v[200:201], v[114:115], v[158:159], v[200:201]
	v_pk_fma_f32 v[202:203], v[116:117], v[160:161], v[202:203]
	v_pk_fma_f32 v[204:205], v[106:107], v[162:163], v[204:205]
	v_pk_fma_f32 v[206:207], v[108:109], v[164:165], v[206:207]
	v_pk_fma_f32 v[208:209], v[102:103], v[166:167], v[208:209]
	v_pk_fma_f32 v[210:211], v[104:105], v[168:169], v[210:211]
	v_pk_fma_f32 v[212:213], v[94:95], v[170:171], v[212:213]
	v_pk_fma_f32 v[214:215], v[96:97], v[172:173], v[214:215]
	global_store_dwordx4 v[234:235], v[200:203], off
	global_store_dwordx4 v[234:235], v[204:207], off offset:64
	global_store_dwordx4 v[234:235], v[208:211], off offset:512
	global_store_dwordx4 v[234:235], v[212:215], off offset:576
	v_lshl_add_u64 v[234:235], v[240:241], 0, v[136:137]
	global_load_dwordx4 v[200:203], v[234:235], off
	global_load_dwordx4 v[204:207], v[234:235], off offset:64
	global_load_dwordx4 v[208:211], v[234:235], off offset:512
	global_load_dwordx4 v[212:215], v[234:235], off offset:576
	s_waitcnt vmcnt(16)
	v_pk_fma_f32 v[216:217], v[98:99], v[158:159], v[216:217]
	v_pk_fma_f32 v[218:219], v[100:101], v[160:161], v[218:219]
	v_pk_fma_f32 v[220:221], v[90:91], v[162:163], v[220:221]
	v_pk_fma_f32 v[222:223], v[92:93], v[164:165], v[222:223]
	v_pk_fma_f32 v[224:225], v[86:87], v[166:167], v[224:225]
	v_pk_fma_f32 v[226:227], v[88:89], v[168:169], v[226:227]
	v_pk_fma_f32 v[228:229], v[82:83], v[170:171], v[228:229]
	v_pk_fma_f32 v[230:231], v[84:85], v[172:173], v[230:231]
	global_store_dwordx4 v[236:237], v[216:219], off
	global_store_dwordx4 v[236:237], v[220:223], off offset:64
	global_store_dwordx4 v[236:237], v[224:227], off offset:512
	global_store_dwordx4 v[236:237], v[228:231], off offset:576
	v_lshl_add_u64 v[236:237], v[240:241], 0, v[138:139]
	global_load_dwordx4 v[216:219], v[236:237], off
	global_load_dwordx4 v[220:223], v[236:237], off offset:64
	global_load_dwordx4 v[224:227], v[236:237], off offset:512
	global_load_dwordx4 v[228:231], v[236:237], off offset:576
	s_waitcnt vmcnt(16)
	v_pk_fma_f32 v[184:185], v[78:79], v[158:159], v[184:185]
	v_pk_fma_f32 v[186:187], v[80:81], v[160:161], v[186:187]
	v_pk_fma_f32 v[188:189], v[74:75], v[162:163], v[188:189]
	v_pk_fma_f32 v[190:191], v[76:77], v[164:165], v[190:191]
	v_pk_fma_f32 v[192:193], v[70:71], v[166:167], v[192:193]
	v_pk_fma_f32 v[194:195], v[72:73], v[168:169], v[194:195]
	v_pk_fma_f32 v[196:197], v[66:67], v[170:171], v[196:197]
	v_pk_fma_f32 v[198:199], v[68:69], v[172:173], v[198:199]
	global_store_dwordx4 v[232:233], v[184:187], off
	global_store_dwordx4 v[232:233], v[188:191], off offset:64
	global_store_dwordx4 v[232:233], v[192:195], off offset:512
	global_store_dwordx4 v[232:233], v[196:199], off offset:576
	v_lshl_add_u64 v[232:233], v[240:241], 0, v[140:141]
	global_load_dwordx4 v[184:187], v[232:233], off
	global_load_dwordx4 v[188:191], v[232:233], off offset:64
	global_load_dwordx4 v[192:195], v[232:233], off offset:512
	global_load_dwordx4 v[196:199], v[232:233], off offset:576
	s_waitcnt vmcnt(16)
	v_pk_fma_f32 v[200:201], v[62:63], v[158:159], v[200:201]
	v_pk_fma_f32 v[202:203], v[64:65], v[160:161], v[202:203]
	v_pk_fma_f32 v[204:205], v[58:59], v[162:163], v[204:205]
	v_pk_fma_f32 v[206:207], v[60:61], v[164:165], v[206:207]
	v_pk_fma_f32 v[208:209], v[54:55], v[166:167], v[208:209]
	v_pk_fma_f32 v[210:211], v[56:57], v[168:169], v[210:211]
	v_pk_fma_f32 v[212:213], v[50:51], v[170:171], v[212:213]
	v_pk_fma_f32 v[214:215], v[52:53], v[172:173], v[214:215]
	global_store_dwordx4 v[234:235], v[200:203], off
	global_store_dwordx4 v[234:235], v[204:207], off offset:64
	global_store_dwordx4 v[234:235], v[208:211], off offset:512
	global_store_dwordx4 v[234:235], v[212:215], off offset:576
	v_lshl_add_u64 v[234:235], v[240:241], 0, v[142:143]
	global_load_dwordx4 v[200:203], v[234:235], off
	global_load_dwordx4 v[204:207], v[234:235], off offset:64
	global_load_dwordx4 v[208:211], v[234:235], off offset:512
	global_load_dwordx4 v[212:215], v[234:235], off offset:576
	s_waitcnt vmcnt(16)
	v_pk_fma_f32 v[216:217], v[46:47], v[158:159], v[216:217]
	v_pk_fma_f32 v[218:219], v[48:49], v[160:161], v[218:219]
	v_pk_fma_f32 v[220:221], v[42:43], v[162:163], v[220:221]
	v_pk_fma_f32 v[222:223], v[44:45], v[164:165], v[222:223]
	v_pk_fma_f32 v[224:225], v[38:39], v[166:167], v[224:225]
	v_pk_fma_f32 v[226:227], v[40:41], v[168:169], v[226:227]
	v_pk_fma_f32 v[228:229], v[34:35], v[170:171], v[228:229]
	v_pk_fma_f32 v[230:231], v[36:37], v[172:173], v[230:231]
	global_store_dwordx4 v[236:237], v[216:219], off
	global_store_dwordx4 v[236:237], v[220:223], off offset:64
	global_store_dwordx4 v[236:237], v[224:227], off offset:512
	global_store_dwordx4 v[236:237], v[228:231], off offset:576
	s_waitcnt vmcnt(12)
	v_pk_fma_f32 v[184:185], v[30:31], v[158:159], v[184:185]
	v_pk_fma_f32 v[186:187], v[32:33], v[160:161], v[186:187]
	v_pk_fma_f32 v[188:189], v[26:27], v[162:163], v[188:189]
	v_pk_fma_f32 v[190:191], v[28:29], v[164:165], v[190:191]
	v_pk_fma_f32 v[192:193], v[22:23], v[166:167], v[192:193]
	v_pk_fma_f32 v[194:195], v[24:25], v[168:169], v[194:195]
	v_pk_fma_f32 v[196:197], v[18:19], v[170:171], v[196:197]
	v_pk_fma_f32 v[198:199], v[20:21], v[172:173], v[198:199]
	global_store_dwordx4 v[232:233], v[184:187], off
	global_store_dwordx4 v[232:233], v[188:191], off offset:64
	global_store_dwordx4 v[232:233], v[192:195], off offset:512
	global_store_dwordx4 v[232:233], v[196:199], off offset:576
	s_waitcnt vmcnt(8)
	v_pk_fma_f32 v[200:201], v[14:15], v[158:159], v[200:201]
	v_pk_fma_f32 v[202:203], v[16:17], v[160:161], v[202:203]
	v_pk_fma_f32 v[204:205], v[10:11], v[162:163], v[204:205]
	v_pk_fma_f32 v[206:207], v[12:13], v[164:165], v[206:207]
	v_pk_fma_f32 v[208:209], v[6:7], v[166:167], v[208:209]
	v_pk_fma_f32 v[210:211], v[8:9], v[168:169], v[210:211]
	v_pk_fma_f32 v[212:213], v[2:3], v[170:171], v[212:213]
	v_pk_fma_f32 v[214:215], v[4:5], v[172:173], v[214:215]
	global_store_dwordx4 v[234:235], v[200:203], off
	global_store_dwordx4 v[234:235], v[204:207], off offset:64
	global_store_dwordx4 v[234:235], v[208:211], off offset:512
	global_store_dwordx4 v[234:235], v[212:215], off offset:576
	s_mov_b64 s[20:21], -1
	s_and_b64 vcc, exec, s[4:5]
	s_cbranch_vccnz .LBB0_1355
	s_andn2_b64 vcc, exec, s[12:13]
	s_cbranch_vccnz .LBB0_1354
	s_barrier
	s_branch .LBB0_1354

.LBB0_2331:
	s_add_i32 s2, s20, 0xffffff80
	s_ashr_i32 s13, s20, 31
	s_cmpk_lt_i32 s20, 0x80
	s_cselect_b32 s23, s13, 0
	s_cselect_b32 s22, s20, s2
	s_cselect_b32 s2, s87, s42
	s_cselect_b32 s13, s86, s41
	s_cselect_b32 s15, s51, 0x4800
	s_lshl_b64 s[22:23], s[22:23], 20
	s_add_u32 s22, s13, s22
	s_addc_u32 s23, s2, s23
	s_cmp_gt_i32 s20, 63
	s_cselect_b32 s2, s15, 0
	v_lshl_or_b32 v86, s21, 8, v177
	s_lshl_b32 s2, s2, 2
	s_add_u32 s20, s43, s2
	v_ashrrev_i32_e32 v87, 31, v86
	s_addc_u32 s21, s44, 0
	v_lshlrev_b64 v[174:175], 2, v[86:87]
	v_lshl_add_u64 v[86:87], s[20:21], 0, v[174:175]
	v_lshl_add_u64 v[174:175], s[22:23], 0, v[174:175]
	v_lshl_add_u64 v[186:187], v[174:175], 0, v[150:151]
	global_load_dwordx4 v[126:129], v[86:87], off
	global_load_dwordx4 v[130:133], v[86:87], off offset:64
	global_load_dwordx4 v[138:141], v[86:87], off offset:512
	global_load_dwordx4 v[182:185], v[86:87], off offset:576
	global_load_dwordx4 v[188:191], v[186:187], off
	global_load_dwordx4 v[192:195], v[186:187], off offset:64
	global_load_dwordx4 v[196:199], v[186:187], off offset:512
	global_load_dwordx4 v[200:203], v[186:187], off offset:576
	v_lshl_add_u64 v[236:237], v[174:175], 0, v[160:161]
	global_load_dwordx4 v[204:207], v[236:237], off
	global_load_dwordx4 v[208:211], v[236:237], off offset:64
	global_load_dwordx4 v[212:215], v[236:237], off offset:512
	global_load_dwordx4 v[216:219], v[236:237], off offset:576
	v_lshl_add_u64 v[240:241], v[174:175], 0, v[162:163]
	global_load_dwordx4 v[220:223], v[240:241], off
	global_load_dwordx4 v[224:227], v[240:241], off offset:64
	global_load_dwordx4 v[228:231], v[240:241], off offset:512
	global_load_dwordx4 v[232:235], v[240:241], off offset:576
	s_waitcnt vmcnt(8)
	v_pk_fma_f32 v[188:189], v[142:143], v[126:127], v[188:189]
	v_pk_fma_f32 v[190:191], v[144:145], v[128:129], v[190:191]
	v_pk_fma_f32 v[192:193], v[134:135], v[130:131], v[192:193]
	v_pk_fma_f32 v[194:195], v[136:137], v[132:133], v[194:195]
	v_pk_fma_f32 v[196:197], v[122:123], v[138:139], v[196:197]
	v_pk_fma_f32 v[198:199], v[124:125], v[140:141], v[198:199]
	v_pk_fma_f32 v[200:201], v[114:115], v[182:183], v[200:201]
	v_pk_fma_f32 v[202:203], v[116:117], v[184:185], v[202:203]
	global_store_dwordx4 v[186:187], v[188:191], off
	global_store_dwordx4 v[186:187], v[192:195], off offset:64
	global_store_dwordx4 v[186:187], v[196:199], off offset:512
	global_store_dwordx4 v[186:187], v[200:203], off offset:576
	v_lshl_add_u64 v[88:89], v[174:175], 0, v[164:165]
	global_load_dwordx4 v[188:191], v[88:89], off
	global_load_dwordx4 v[192:195], v[88:89], off offset:64
	global_load_dwordx4 v[196:199], v[88:89], off offset:512
	global_load_dwordx4 v[200:203], v[88:89], off offset:576
	s_waitcnt vmcnt(12)
	v_pk_fma_f32 v[204:205], v[118:119], v[126:127], v[204:205]
	v_pk_fma_f32 v[206:207], v[120:121], v[128:129], v[206:207]
	v_pk_fma_f32 v[208:209], v[110:111], v[130:131], v[208:209]
	v_pk_fma_f32 v[210:211], v[112:113], v[132:133], v[210:211]
	v_pk_fma_f32 v[212:213], v[106:107], v[138:139], v[212:213]
	v_pk_fma_f32 v[214:215], v[108:109], v[140:141], v[214:215]
	v_pk_fma_f32 v[216:217], v[98:99], v[182:183], v[216:217]
	v_pk_fma_f32 v[218:219], v[100:101], v[184:185], v[218:219]
	global_store_dwordx4 v[236:237], v[204:207], off
	global_store_dwordx4 v[236:237], v[208:211], off offset:64
	global_store_dwordx4 v[236:237], v[212:215], off offset:512
	global_store_dwordx4 v[236:237], v[216:219], off offset:576
	v_lshl_add_u64 v[236:237], v[174:175], 0, v[152:153]
	global_load_dwordx4 v[204:207], v[236:237], off
	global_load_dwordx4 v[208:211], v[236:237], off offset:64
	global_load_dwordx4 v[212:215], v[236:237], off offset:512
	global_load_dwordx4 v[216:219], v[236:237], off offset:576
	s_waitcnt vmcnt(16)
	v_pk_fma_f32 v[220:221], v[102:103], v[126:127], v[220:221]
	v_pk_fma_f32 v[222:223], v[104:105], v[128:129], v[222:223]
	v_pk_fma_f32 v[224:225], v[94:95], v[130:131], v[224:225]
	v_pk_fma_f32 v[226:227], v[96:97], v[132:133], v[226:227]
	v_pk_fma_f32 v[228:229], v[90:91], v[138:139], v[228:229]
	v_pk_fma_f32 v[230:231], v[92:93], v[140:141], v[230:231]
	v_pk_fma_f32 v[232:233], v[78:79], v[182:183], v[232:233]
	v_pk_fma_f32 v[234:235], v[80:81], v[184:185], v[234:235]
	global_store_dwordx4 v[240:241], v[220:223], off
	global_store_dwordx4 v[240:241], v[224:227], off offset:64
	global_store_dwordx4 v[240:241], v[228:231], off offset:512
	global_store_dwordx4 v[240:241], v[232:235], off offset:576
	v_lshl_add_u64 v[240:241], v[174:175], 0, v[154:155]
	global_load_dwordx4 v[220:223], v[240:241], off
	global_load_dwordx4 v[224:227], v[240:241], off offset:64
	global_load_dwordx4 v[228:231], v[240:241], off offset:512
	global_load_dwordx4 v[232:235], v[240:241], off offset:576
	s_waitcnt vmcnt(16)
	v_pk_fma_f32 v[188:189], v[82:83], v[126:127], v[188:189]
	v_pk_fma_f32 v[190:191], v[84:85], v[128:129], v[190:191]
	v_pk_fma_f32 v[192:193], v[74:75], v[130:131], v[192:193]
	v_pk_fma_f32 v[194:195], v[76:77], v[132:133], v[194:195]
	v_pk_fma_f32 v[196:197], v[70:71], v[138:139], v[196:197]
	v_pk_fma_f32 v[198:199], v[72:73], v[140:141], v[198:199]
	v_pk_fma_f32 v[200:201], v[66:67], v[182:183], v[200:201]
	v_pk_fma_f32 v[202:203], v[68:69], v[184:185], v[202:203]
	global_store_dwordx4 v[88:89], v[188:191], off
	global_store_dwordx4 v[88:89], v[192:195], off offset:64
	global_store_dwordx4 v[88:89], v[196:199], off offset:512
	global_store_dwordx4 v[88:89], v[200:203], off offset:576
	v_lshl_add_u64 v[88:89], v[174:175], 0, v[156:157]
	global_load_dwordx4 v[188:191], v[88:89], off
	global_load_dwordx4 v[192:195], v[88:89], off offset:64
	global_load_dwordx4 v[196:199], v[88:89], off offset:512
	global_load_dwordx4 v[200:203], v[88:89], off offset:576
	s_waitcnt vmcnt(16)
	v_pk_fma_f32 v[204:205], v[62:63], v[126:127], v[204:205]
	v_pk_fma_f32 v[206:207], v[64:65], v[128:129], v[206:207]
	v_pk_fma_f32 v[208:209], v[58:59], v[130:131], v[208:209]
	v_pk_fma_f32 v[210:211], v[60:61], v[132:133], v[210:211]
	v_pk_fma_f32 v[212:213], v[54:55], v[138:139], v[212:213]
	v_pk_fma_f32 v[214:215], v[56:57], v[140:141], v[214:215]
	v_pk_fma_f32 v[216:217], v[50:51], v[182:183], v[216:217]
	v_pk_fma_f32 v[218:219], v[52:53], v[184:185], v[218:219]
	global_store_dwordx4 v[236:237], v[204:207], off
	global_store_dwordx4 v[236:237], v[208:211], off offset:64
	global_store_dwordx4 v[236:237], v[212:215], off offset:512
	global_store_dwordx4 v[236:237], v[216:219], off offset:576
	v_lshl_add_u64 v[236:237], v[174:175], 0, v[158:159]
	global_load_dwordx4 v[204:207], v[236:237], off
	global_load_dwordx4 v[208:211], v[236:237], off offset:64
	global_load_dwordx4 v[212:215], v[236:237], off offset:512
	global_load_dwordx4 v[216:219], v[236:237], off offset:576
	s_waitcnt vmcnt(16)
	v_pk_fma_f32 v[220:221], v[46:47], v[126:127], v[220:221]
	v_pk_fma_f32 v[222:223], v[48:49], v[128:129], v[222:223]
	v_pk_fma_f32 v[224:225], v[42:43], v[130:131], v[224:225]
	v_pk_fma_f32 v[226:227], v[44:45], v[132:133], v[226:227]
	v_pk_fma_f32 v[228:229], v[38:39], v[138:139], v[228:229]
	v_pk_fma_f32 v[230:231], v[40:41], v[140:141], v[230:231]
	v_pk_fma_f32 v[232:233], v[34:35], v[182:183], v[232:233]
	v_pk_fma_f32 v[234:235], v[36:37], v[184:185], v[234:235]
	global_store_dwordx4 v[240:241], v[220:223], off
	global_store_dwordx4 v[240:241], v[224:227], off offset:64
	global_store_dwordx4 v[240:241], v[228:231], off offset:512
	global_store_dwordx4 v[240:241], v[232:235], off offset:576
	s_waitcnt vmcnt(12)
	v_pk_fma_f32 v[188:189], v[30:31], v[126:127], v[188:189]
	v_pk_fma_f32 v[190:191], v[32:33], v[128:129], v[190:191]
	v_pk_fma_f32 v[192:193], v[26:27], v[130:131], v[192:193]
	v_pk_fma_f32 v[194:195], v[28:29], v[132:133], v[194:195]
	v_pk_fma_f32 v[196:197], v[22:23], v[138:139], v[196:197]
	v_pk_fma_f32 v[198:199], v[24:25], v[140:141], v[198:199]
	v_pk_fma_f32 v[200:201], v[14:15], v[182:183], v[200:201]
	v_pk_fma_f32 v[202:203], v[16:17], v[184:185], v[202:203]
	global_store_dwordx4 v[88:89], v[188:191], off
	global_store_dwordx4 v[88:89], v[192:195], off offset:64
	global_store_dwordx4 v[88:89], v[196:199], off offset:512
	global_store_dwordx4 v[88:89], v[200:203], off offset:576
	s_waitcnt vmcnt(8)
	v_pk_fma_f32 v[204:205], v[18:19], v[126:127], v[204:205]
	v_pk_fma_f32 v[206:207], v[20:21], v[128:129], v[206:207]
	v_pk_fma_f32 v[208:209], v[10:11], v[130:131], v[208:209]
	v_pk_fma_f32 v[210:211], v[12:13], v[132:133], v[210:211]
	v_pk_fma_f32 v[212:213], v[6:7], v[138:139], v[212:213]
	v_pk_fma_f32 v[214:215], v[8:9], v[140:141], v[214:215]
	v_pk_fma_f32 v[216:217], v[2:3], v[182:183], v[216:217]
	v_pk_fma_f32 v[218:219], v[4:5], v[184:185], v[218:219]
	global_store_dwordx4 v[236:237], v[204:207], off
	global_store_dwordx4 v[236:237], v[208:211], off offset:64
	global_store_dwordx4 v[236:237], v[212:215], off offset:512
	global_store_dwordx4 v[236:237], v[216:219], off offset:576
	s_mov_b64 s[20:21], -1
	s_andn2_b64 vcc, exec, s[4:5]
	s_cbranch_vccnz .LBB0_2320
	s_andn2_b64 vcc, exec, s[6:7]
	s_cbranch_vccnz .LBB0_2319
	s_barrier
	s_branch .LBB0_2319

.LBB0_2586:
	s_add_i32 s2, s48, 0xffffff80
	s_ashr_i32 s16, s48, 31
	s_cmpk_lt_i32 s48, 0x80
	s_cselect_b32 s17, s16, 0
	s_cselect_b32 s16, s48, s2
	s_cselect_b32 s2, s87, s36
	s_cselect_b32 s18, s86, s35
	s_cselect_b32 s19, s45, 0x4800
	s_lshl_b64 s[16:17], s[16:17], 20
	s_add_u32 s16, s18, s16
	s_addc_u32 s17, s2, s17
	s_cmp_gt_i32 s48, 63
	s_cselect_b32 s2, s19, 0
	v_lshl_or_b32 v158, s49, 8, v177
	s_lshl_b32 s2, s2, 2
	s_add_u32 s18, s37, s2
	v_ashrrev_i32_e32 v159, 31, v158
	s_addc_u32 s19, s38, 0
	v_lshlrev_b64 v[174:175], 2, v[158:159]
	v_lshl_add_u64 v[182:183], s[18:19], 0, v[174:175]
	global_load_dwordx4 v[158:161], v[182:183], off
	global_load_dwordx4 v[162:165], v[182:183], off offset:64
	global_load_dwordx4 v[166:169], v[182:183], off offset:512
	global_load_dwordx4 v[170:173], v[182:183], off offset:576
	v_lshl_add_u64 v[240:241], s[16:17], 0, v[174:175]
	v_lshl_add_u64 v[232:233], v[240:241], 0, v[134:135]
	global_load_dwordx4 v[184:187], v[232:233], off
	global_load_dwordx4 v[188:191], v[232:233], off offset:64
	global_load_dwordx4 v[192:195], v[232:233], off offset:512
	global_load_dwordx4 v[196:199], v[232:233], off offset:576
	v_lshl_add_u64 v[234:235], v[240:241], 0, v[144:145]
	global_load_dwordx4 v[200:203], v[234:235], off
	global_load_dwordx4 v[204:207], v[234:235], off offset:64
	global_load_dwordx4 v[208:211], v[234:235], off offset:512
	global_load_dwordx4 v[212:215], v[234:235], off offset:576
	v_lshl_add_u64 v[236:237], v[240:241], 0, v[146:147]
	global_load_dwordx4 v[216:219], v[236:237], off
	global_load_dwordx4 v[220:223], v[236:237], off offset:64
	global_load_dwordx4 v[224:227], v[236:237], off offset:512
	global_load_dwordx4 v[228:231], v[236:237], off offset:576
	s_waitcnt vmcnt(8)
	v_pk_mul_f32 v[158:159], v[158:159], 0.5 op_sel_hi:[1,0]
	v_pk_mul_f32 v[160:161], v[160:161], 0.5 op_sel_hi:[1,0]
	v_pk_mul_f32 v[162:163], v[162:163], 0.5 op_sel_hi:[1,0]
	v_pk_mul_f32 v[164:165], v[164:165], 0.5 op_sel_hi:[1,0]
	v_pk_mul_f32 v[166:167], v[166:167], 0.5 op_sel_hi:[1,0]
	v_pk_mul_f32 v[168:169], v[168:169], 0.5 op_sel_hi:[1,0]
	v_pk_mul_f32 v[170:171], v[170:171], 0.5 op_sel_hi:[1,0]
	v_pk_mul_f32 v[172:173], v[172:173], 0.5 op_sel_hi:[1,0]
	v_pk_fma_f32 v[184:185], v[126:127], v[158:159], v[184:185]
	v_pk_fma_f32 v[186:187], v[128:129], v[160:161], v[186:187]
	v_pk_fma_f32 v[188:189], v[122:123], v[162:163], v[188:189]
	v_pk_fma_f32 v[190:191], v[124:125], v[164:165], v[190:191]
	v_pk_fma_f32 v[192:193], v[118:119], v[166:167], v[192:193]
	v_pk_fma_f32 v[194:195], v[120:121], v[168:169], v[194:195]
	v_pk_fma_f32 v[196:197], v[110:111], v[170:171], v[196:197]
	v_pk_fma_f32 v[198:199], v[112:113], v[172:173], v[198:199]
	global_store_dwordx4 v[232:233], v[184:187], off
	global_store_dwordx4 v[232:233], v[188:191], off offset:64
	global_store_dwordx4 v[232:233], v[192:195], off offset:512
	global_store_dwordx4 v[232:233], v[196:199], off offset:576
	v_lshl_add_u64 v[232:233], v[240:241], 0, v[148:149]
	global_load_dwordx4 v[184:187], v[232:233], off
	global_load_dwordx4 v[188:191], v[232:233], off offset:64
	global_load_dwordx4 v[192:195], v[232:233], off offset:512
	global_load_dwordx4 v[196:199], v[232:233], off offset:576
	s_waitcnt vmcnt(12)
	v_pk_fma_f32 v[200:201], v[114:115], v[158:159], v[200:201]
	v_pk_fma_f32 v[202:203], v[116:117], v[160:161], v[202:203]
	v_pk_fma_f32 v[204:205], v[106:107], v[162:163], v[204:205]
	v_pk_fma_f32 v[206:207], v[108:109], v[164:165], v[206:207]
	v_pk_fma_f32 v[208:209], v[102:103], v[166:167], v[208:209]
	v_pk_fma_f32 v[210:211], v[104:105], v[168:169], v[210:211]
	v_pk_fma_f32 v[212:213], v[94:95], v[170:171], v[212:213]
	v_pk_fma_f32 v[214:215], v[96:97], v[172:173], v[214:215]
	global_store_dwordx4 v[234:235], v[200:203], off
	global_store_dwordx4 v[234:235], v[204:207], off offset:64
	global_store_dwordx4 v[234:235], v[208:211], off offset:512
	global_store_dwordx4 v[234:235], v[212:215], off offset:576
	v_lshl_add_u64 v[234:235], v[240:241], 0, v[136:137]
	global_load_dwordx4 v[200:203], v[234:235], off
	global_load_dwordx4 v[204:207], v[234:235], off offset:64
	global_load_dwordx4 v[208:211], v[234:235], off offset:512
	global_load_dwordx4 v[212:215], v[234:235], off offset:576
	s_waitcnt vmcnt(16)
	v_pk_fma_f32 v[216:217], v[98:99], v[158:159], v[216:217]
	v_pk_fma_f32 v[218:219], v[100:101], v[160:161], v[218:219]
	v_pk_fma_f32 v[220:221], v[90:91], v[162:163], v[220:221]
	v_pk_fma_f32 v[222:223], v[92:93], v[164:165], v[222:223]
	v_pk_fma_f32 v[224:225], v[86:87], v[166:167], v[224:225]
	v_pk_fma_f32 v[226:227], v[88:89], v[168:169], v[226:227]
	v_pk_fma_f32 v[228:229], v[82:83], v[170:171], v[228:229]
	v_pk_fma_f32 v[230:231], v[84:85], v[172:173], v[230:231]
	global_store_dwordx4 v[236:237], v[216:219], off
	global_store_dwordx4 v[236:237], v[220:223], off offset:64
	global_store_dwordx4 v[236:237], v[224:227], off offset:512
	global_store_dwordx4 v[236:237], v[228:231], off offset:576
	v_lshl_add_u64 v[236:237], v[240:241], 0, v[138:139]
	global_load_dwordx4 v[216:219], v[236:237], off
	global_load_dwordx4 v[220:223], v[236:237], off offset:64
	global_load_dwordx4 v[224:227], v[236:237], off offset:512
	global_load_dwordx4 v[228:231], v[236:237], off offset:576
	s_waitcnt vmcnt(16)
	v_pk_fma_f32 v[184:185], v[78:79], v[158:159], v[184:185]
	v_pk_fma_f32 v[186:187], v[80:81], v[160:161], v[186:187]
	v_pk_fma_f32 v[188:189], v[74:75], v[162:163], v[188:189]
	v_pk_fma_f32 v[190:191], v[76:77], v[164:165], v[190:191]
	v_pk_fma_f32 v[192:193], v[70:71], v[166:167], v[192:193]
	v_pk_fma_f32 v[194:195], v[72:73], v[168:169], v[194:195]
	v_pk_fma_f32 v[196:197], v[66:67], v[170:171], v[196:197]
	v_pk_fma_f32 v[198:199], v[68:69], v[172:173], v[198:199]
	global_store_dwordx4 v[232:233], v[184:187], off
	global_store_dwordx4 v[232:233], v[188:191], off offset:64
	global_store_dwordx4 v[232:233], v[192:195], off offset:512
	global_store_dwordx4 v[232:233], v[196:199], off offset:576
	v_lshl_add_u64 v[232:233], v[240:241], 0, v[140:141]
	global_load_dwordx4 v[184:187], v[232:233], off
	global_load_dwordx4 v[188:191], v[232:233], off offset:64
	global_load_dwordx4 v[192:195], v[232:233], off offset:512
	global_load_dwordx4 v[196:199], v[232:233], off offset:576
	s_waitcnt vmcnt(16)
	v_pk_fma_f32 v[200:201], v[62:63], v[158:159], v[200:201]
	v_pk_fma_f32 v[202:203], v[64:65], v[160:161], v[202:203]
	v_pk_fma_f32 v[204:205], v[58:59], v[162:163], v[204:205]
	v_pk_fma_f32 v[206:207], v[60:61], v[164:165], v[206:207]
	v_pk_fma_f32 v[208:209], v[54:55], v[166:167], v[208:209]
	v_pk_fma_f32 v[210:211], v[56:57], v[168:169], v[210:211]
	v_pk_fma_f32 v[212:213], v[50:51], v[170:171], v[212:213]
	v_pk_fma_f32 v[214:215], v[52:53], v[172:173], v[214:215]
	global_store_dwordx4 v[234:235], v[200:203], off
	global_store_dwordx4 v[234:235], v[204:207], off offset:64
	global_store_dwordx4 v[234:235], v[208:211], off offset:512
	global_store_dwordx4 v[234:235], v[212:215], off offset:576
	v_lshl_add_u64 v[234:235], v[240:241], 0, v[142:143]
	global_load_dwordx4 v[200:203], v[234:235], off
	global_load_dwordx4 v[204:207], v[234:235], off offset:64
	global_load_dwordx4 v[208:211], v[234:235], off offset:512
	global_load_dwordx4 v[212:215], v[234:235], off offset:576
	s_waitcnt vmcnt(16)
	v_pk_fma_f32 v[216:217], v[46:47], v[158:159], v[216:217]
	v_pk_fma_f32 v[218:219], v[48:49], v[160:161], v[218:219]
	v_pk_fma_f32 v[220:221], v[42:43], v[162:163], v[220:221]
	v_pk_fma_f32 v[222:223], v[44:45], v[164:165], v[222:223]
	v_pk_fma_f32 v[224:225], v[38:39], v[166:167], v[224:225]
	v_pk_fma_f32 v[226:227], v[40:41], v[168:169], v[226:227]
	v_pk_fma_f32 v[228:229], v[30:31], v[170:171], v[228:229]
	v_pk_fma_f32 v[230:231], v[32:33], v[172:173], v[230:231]
	global_store_dwordx4 v[236:237], v[216:219], off
	global_store_dwordx4 v[236:237], v[220:223], off offset:64
	global_store_dwordx4 v[236:237], v[224:227], off offset:512
	global_store_dwordx4 v[236:237], v[228:231], off offset:576
	s_waitcnt vmcnt(12)
	v_pk_fma_f32 v[184:185], v[34:35], v[158:159], v[184:185]
	v_pk_fma_f32 v[186:187], v[36:37], v[160:161], v[186:187]
	v_pk_fma_f32 v[188:189], v[26:27], v[162:163], v[188:189]
	v_pk_fma_f32 v[190:191], v[28:29], v[164:165], v[190:191]
	v_pk_fma_f32 v[192:193], v[22:23], v[166:167], v[192:193]
	v_pk_fma_f32 v[194:195], v[24:25], v[168:169], v[194:195]
	v_pk_fma_f32 v[196:197], v[14:15], v[170:171], v[196:197]
	v_pk_fma_f32 v[198:199], v[16:17], v[172:173], v[198:199]
	global_store_dwordx4 v[232:233], v[184:187], off
	global_store_dwordx4 v[232:233], v[188:191], off offset:64
	global_store_dwordx4 v[232:233], v[192:195], off offset:512
	global_store_dwordx4 v[232:233], v[196:199], off offset:576
	s_waitcnt vmcnt(8)
	v_pk_fma_f32 v[200:201], v[18:19], v[158:159], v[200:201]
	v_pk_fma_f32 v[202:203], v[20:21], v[160:161], v[202:203]
	v_pk_fma_f32 v[204:205], v[10:11], v[162:163], v[204:205]
	v_pk_fma_f32 v[206:207], v[12:13], v[164:165], v[206:207]
	v_pk_fma_f32 v[208:209], v[6:7], v[166:167], v[208:209]
	v_pk_fma_f32 v[210:211], v[8:9], v[168:169], v[210:211]
	v_pk_fma_f32 v[212:213], v[2:3], v[170:171], v[212:213]
	v_pk_fma_f32 v[214:215], v[4:5], v[172:173], v[214:215]
	global_store_dwordx4 v[234:235], v[200:203], off
	global_store_dwordx4 v[234:235], v[204:207], off offset:64
	global_store_dwordx4 v[234:235], v[208:211], off offset:512
	global_store_dwordx4 v[234:235], v[212:215], off offset:576
	s_mov_b64 s[16:17], -1
	s_and_b64 vcc, exec, s[4:5]
	s_cbranch_vccnz .LBB0_2571
	s_andn2_b64 vcc, exec, s[8:9]
	s_cbranch_vccnz .LBB0_2570
	s_barrier
	s_branch .LBB0_2570

	.amdhsa_kernel _Z8mega_fwd4Args
		.amdhsa_group_segment_fixed_size 0
		.amdhsa_private_segment_fixed_size 0
		.amdhsa_kernarg_size 544
		.amdhsa_user_sgpr_count 2
		.amdhsa_user_sgpr_dispatch_ptr 0
		.amdhsa_user_sgpr_queue_ptr 0
		.amdhsa_user_sgpr_kernarg_segment_ptr 1
		.amdhsa_user_sgpr_dispatch_id 0
		.amdhsa_user_sgpr_kernarg_preload_length 0
		.amdhsa_user_sgpr_kernarg_preload_offset 0
		.amdhsa_user_sgpr_private_segment_size 0
		.amdhsa_uses_dynamic_stack 0
		.amdhsa_enable_private_segment 0
		.amdhsa_system_sgpr_workgroup_id_x 1
		.amdhsa_system_sgpr_workgroup_id_y 0
		.amdhsa_system_sgpr_workgroup_id_z 0
		.amdhsa_system_sgpr_workgroup_info 0
		.amdhsa_system_vgpr_workitem_id 2
		.amdhsa_next_free_vgpr 256
		.amdhsa_next_free_sgpr 98
		.amdhsa_accum_offset 256
		.amdhsa_reserve_vcc 1
		.amdhsa_float_round_mode_32 0
		.amdhsa_float_round_mode_16_64 0
		.amdhsa_float_denorm_mode_32 3
		.amdhsa_float_denorm_mode_16_64 3
		.amdhsa_dx10_clamp 1
		.amdhsa_ieee_mode 1
		.amdhsa_fp16_overflow 0
		.amdhsa_tg_split 0
		.amdhsa_exception_fp_ieee_invalid_op 0
		.amdhsa_exception_fp_denorm_src 0
		.amdhsa_exception_fp_ieee_div_zero 0
		.amdhsa_exception_fp_ieee_overflow 0
		.amdhsa_exception_fp_ieee_underflow 0
		.amdhsa_exception_fp_ieee_inexact 0
		.amdhsa_exception_int_div_zero 0
	.end_amdhsa_kernel

amdhsa.kernels:
  - .agpr_count:     0
    .args:
      - .offset:         0
        .size:           288
        .value_kind:     by_value
      - .offset:         288
        .size:           4
        .value_kind:     hidden_block_count_x
      - .offset:         292
        .size:           4
        .value_kind:     hidden_block_count_y
      - .offset:         296
        .size:           4
        .value_kind:     hidden_block_count_z
      - .offset:         300
        .size:           2
        .value_kind:     hidden_group_size_x
      - .offset:         302
        .size:           2
        .value_kind:     hidden_group_size_y
      - .offset:         304
        .size:           2
        .value_kind:     hidden_group_size_z
      - .offset:         306
        .size:           2
        .value_kind:     hidden_remainder_x
      - .offset:         308
        .size:           2
        .value_kind:     hidden_remainder_y
      - .offset:         310
        .size:           2
        .value_kind:     hidden_remainder_z
      - .offset:         328
        .size:           8
        .value_kind:     hidden_global_offset_x
      - .offset:         336
        .size:           8
        .value_kind:     hidden_global_offset_y
      - .offset:         344
        .size:           8
        .value_kind:     hidden_global_offset_z
      - .offset:         352
        .size:           2
        .value_kind:     hidden_grid_dims
      - .offset:         376
        .size:           8
        .value_kind:     hidden_multigrid_sync_arg
      - .offset:         408
        .size:           4
        .value_kind:     hidden_dynamic_lds_size
    .group_segment_fixed_size: 0
    .kernarg_segment_align: 8
    .kernarg_segment_size: 544
    .language:       OpenCL C
    .language_version:
      - 2
      - 0
    .max_flat_workgroup_size: 512
    .name:           _Z8mega_fwd4Args
    .private_segment_fixed_size: 0
    .sgpr_count:     104
    .sgpr_spill_count: 96
    .symbol:         _Z8mega_fwd4Args.kd
    .uniform_work_group_size: 1
    .uses_dynamic_stack: false
    .vgpr_count:     256
    .vgpr_spill_count: 0
    .wavefront_size: 64
